# gla_scan fast loop: own registers for the fragment reads of MFMA rounds 2/3 and for the 8 state-image reads (issued ahead, counted lgkmcnt) instead of serial reuse of two register sets; lru loop waits
# speedup vs baseline: 1.0399x; 1.0103x over previous
; DI void phase_gla_scan(const Params& p, LAS unsigned char* lds) {
;     ...
;         auto lstore = [&](int buf, const u32x4 (&rk)[4], const u32x4& rv, const float& rt) {
;             LAS unsigned char* sb = lds + buf * SET;
; #pragma unroll
;             for (int i = 0; i < 4; ++i) { const int idx = tid + i * 512, row = idx >> 5, cc = idx & 31; *(LAS u32x4*)(sb + row * KR + cc * 16) = rk[i]; }
;             if (tid < 256) { const int row = tid >> 2, cc = tid & 3; *(LAS u32x4*)(sb + 64 * KR + row * VR + cc * 16) = rv; ((LAS float*)(sb + 64 * KR + 64 * VR))[tid] = __expf(rt); }
;     ...
;         auto step = [&](int c, const bf16x8 (&qc)[8]) {
;             LAS unsigned char* sb = lds + (c & 1) * SET; LAS unsigned char* stb = lds + ST_OFF + (c & 1) * STB;
; #pragma unroll
;             for (int g = 0; g < 4; ++g) { const f32x4 e = *(LAS const f32x4*)(sb + 64 * KR + 64 * VR + (32 * w + 8 * g + 4 * hh) * 4);
;                 st[4 * g] *= e[0]; st[4 * g + 1] *= e[1]; st[4 * g + 2] *= e[2]; st[4 * g + 3] *= e[3]; }
; #pragma unroll
;             for (int sx = 0; sx < 4; ++sx) {
;                 LAS unsigned char* ka = sb + (16 * sx + 8 * hh + tq) * KR + (32 * w + 16 * blk + 4 * tp) * 2;
;                 LAS unsigned char* va = sb + 64 * KR + (16 * sx + 8 * hh + tq) * VR + (16 * blk + 4 * tp) * 2;
;                 const bf16x8 af = cat4(trread(ka), trread(ka + 4 * KR)), bfv = cat4(trread(va), trread(va + 4 * VR));
;                 st = mfma32(af, bfv, st);
;             }
; #pragma unroll
;             for (int g = 0; g < 4; ++g) { u32x2 wv; wv.x = pk2(st[4 * g], st[4 * g + 1]); wv.y = pk2(st[4 * g + 2], st[4 * g + 3]);
;                 *(LAS u32x2*)(stb + l32 * SR + (32 * w + 8 * g + 4 * hh) * 2) = wv; }
;             asm volatile("s_waitcnt lgkmcnt(0)" ::: "memory");
;             __builtin_amdgcn_s_barrier();
;             asm volatile("" ::: "memory");
;             f32x4 acc = {0.f, 0.f, 0.f, 0.f};
; #pragma unroll
;             for (int ks = 0; ks < 8; ++ks) {
;                 const bf16x8 bb = *(LAS const bf16x8*)(stb + (16 * nt + i16) * SR + (32 * ks + 8 * quad) * 2);
;                 acc = __builtin_amdgcn_mfma_f32_16x16x32_bf16(qc[ks], bb, acc, 0, 0, 0);
;             }
; #pragma unroll
;             for (int jj = 0; jj < 4; ++jj) ob[(tok0 + c * 64 + 16 * mt + quad * 4 + jj) * DM + h * 512 + vs * 32 + 16 * nt + i16] = f2bf(acc[jj] * (1.f / 16.f));
;         };
.Lgs_592:
	ds_read_b128 v[198:201], v169 offset:41056
	ds_read_b128 v[202:205], v169 offset:41024
	ds_read_b128 v[206:209], v169 offset:40960
	ds_read_b128 v[210:213], v169 offset:40992
	ds_read_b64_tr_b16 v[214:215], v190
	ds_read_b64_tr_b16 v[216:217], v190 offset:2304
	ds_read_b64_tr_b16 v[218:219], v170 offset:36864
	ds_read_b64_tr_b16 v[220:221], v170 offset:37120
	s_waitcnt lgkmcnt(7)
	v_pk_mul_f32 v[12:13], v[12:13], v[198:199]
	s_waitcnt lgkmcnt(6)
	v_pk_mul_f32 v[8:9], v[8:9], v[202:203]
	s_waitcnt lgkmcnt(4)
	v_pk_mul_f32 v[4:5], v[4:5], v[210:211]
	v_pk_mul_f32 v[0:1], v[0:1], v[206:207]
	v_pk_mul_f32 v[14:15], v[14:15], v[200:201]
	v_pk_mul_f32 v[10:11], v[10:11], v[204:205]
	v_pk_mul_f32 v[6:7], v[6:7], v[212:213]
	v_pk_mul_f32 v[2:3], v[2:3], v[208:209]
	ds_read_b64_tr_b16 v[198:199], v191
	ds_read_b64_tr_b16 v[200:201], v191 offset:2304
	ds_read_b64_tr_b16 v[202:203], v171 offset:36864
	ds_read_b64_tr_b16 v[204:205], v171 offset:37120
	ds_read_b64_tr_b16 v[222:223], v192
	ds_read_b64_tr_b16 v[224:225], v192 offset:2304
	ds_read_b64_tr_b16 v[226:227], v172 offset:36864
	ds_read_b64_tr_b16 v[228:229], v172 offset:37120
	s_waitcnt lgkmcnt(8)
	v_mfma_f32_32x32x16_bf16 v[0:15], v[214:217], v[218:221], v[0:15]
	s_cmp_gt_u32 s24, 61
	s_cselect_b64 s[34:35], -1, 0
	ds_read_b64_tr_b16 v[230:231], v193
	ds_read_b64_tr_b16 v[232:233], v193 offset:2304
	ds_read_b64_tr_b16 v[234:235], v173 offset:36864
	ds_read_b64_tr_b16 v[236:237], v173 offset:37120
	s_waitcnt lgkmcnt(8)
	v_mfma_f32_32x32x16_bf16 v[0:15], v[198:201], v[202:205], v[0:15]
	s_waitcnt lgkmcnt(4)
	v_mfma_f32_32x32x16_bf16 v[0:15], v[222:225], v[226:229], v[0:15]
	s_waitcnt lgkmcnt(0)
	v_mfma_f32_32x32x16_bf16 v[0:15], v[230:233], v[234:237], v[0:15]
	s_nop 11
	v_cvt_pk_bf16_f32 v158, v0, v1
	v_cvt_pk_bf16_f32 v159, v2, v3
	v_cvt_pk_bf16_f32 v198, v4, v5
	v_cvt_pk_bf16_f32 v199, v6, v7
	v_cvt_pk_bf16_f32 v200, v8, v9
	v_cvt_pk_bf16_f32 v201, v10, v11
	v_cvt_pk_bf16_f32 v202, v12, v13
	v_cvt_pk_bf16_f32 v203, v14, v15
	ds_write2_b64 v174, v[158:159], v[198:199] offset1:2
	ds_write2_b64 v174, v[200:201], v[202:203] offset0:4 offset1:6
	s_waitcnt lgkmcnt(0)
	s_barrier
	ds_read_b128 v[222:225], v175
	ds_read_b128 v[226:229], v175 offset:64
	ds_read_b128 v[230:233], v175 offset:128
	ds_read_b128 v[234:237], v175 offset:192
	ds_read_b128 v[238:241], v175 offset:256
	ds_read_b128 v[242:245], v175 offset:320
	ds_read_b128 v[246:249], v175 offset:384
	ds_read_b128 v[250:253], v175 offset:448
	s_waitcnt vmcnt(27) lgkmcnt(7)
	v_mfma_f32_16x16x32_bf16 v[198:201], v[56:59], v[222:225], 0
	v_lshl_add_u64 v[158:159], s[12:13], 0, v[148:149]
	v_add_co_u32_e32 v210, vcc, s45, v158
	s_waitcnt vmcnt(26) lgkmcnt(6)
	v_mfma_f32_16x16x32_bf16 v[198:201], v[60:63], v[226:229], v[198:201]
	v_addc_co_u32_e32 v211, vcc, 0, v159, vcc
	s_waitcnt vmcnt(25) lgkmcnt(5)
	v_mfma_f32_16x16x32_bf16 v[198:201], v[64:67], v[230:233], v[198:201]
	v_lshl_add_u64 v[212:213], v[158:159], 0, s[98:99]
	s_waitcnt vmcnt(24) lgkmcnt(4)
	v_mfma_f32_16x16x32_bf16 v[198:201], v[68:71], v[234:237], v[198:201]
	s_waitcnt vmcnt(23) lgkmcnt(3)
	v_mfma_f32_16x16x32_bf16 v[198:201], v[72:75], v[238:241], v[198:201]
	v_lshl_add_u64 v[158:159], v[158:159], 0, s[100:101]
	s_waitcnt vmcnt(22) lgkmcnt(2)
	v_mfma_f32_16x16x32_bf16 v[198:201], v[80:83], v[242:245], v[198:201]
	s_waitcnt vmcnt(21) lgkmcnt(1)
	v_mfma_f32_16x16x32_bf16 v[198:201], v[88:91], v[246:249], v[198:201]
	s_and_b64 vcc, exec, s[34:35]
	s_waitcnt vmcnt(20) lgkmcnt(0)
	v_mfma_f32_16x16x32_bf16 v[198:201], v[96:99], v[250:253], v[198:201]
	s_nop 7
	v_mul_f32_e32 v130, 0x3d800000, v198
	v_mul_f32_e32 v197, 0x3d800000, v199
	v_mul_f32_e32 v199, 0x3d800000, v201
	v_mul_f32_e32 v198, 0x3d800000, v200
	v_cvt_pk_bf16_f32 v130, v130, s0
	v_cvt_pk_bf16_f32 v199, v199, s0
	v_cvt_pk_bf16_f32 v197, v197, s0
	v_cvt_pk_bf16_f32 v198, v198, s0
	global_store_short v[210:211], v130, off offset:-4096
	global_store_short v[210:211], v197, off
	global_store_short v[212:213], v198, off
	global_store_short v[158:159], v199, off
	v_lshl_add_u64 v[158:159], s[12:13], 0, v[144:145]
	s_cbranch_vccnz .Lgs_596
	v_lshl_add_u64 v[96:97], v[158:159], 0, s[96:97]
	global_load_dwordx4 v[56:59], v[96:97], off
	global_load_dwordx4 v[60:63], v[96:97], off offset:64
	global_load_dwordx4 v[64:67], v[96:97], off offset:128
	global_load_dwordx4 v[68:71], v[96:97], off offset:192
	global_load_dwordx4 v[72:75], v[96:97], off offset:256
	global_load_dwordx4 v[80:83], v[96:97], off offset:320
	global_load_dwordx4 v[88:91], v[96:97], off offset:384
	s_nop 0
	global_load_dwordx4 v[96:99], v[96:97], off offset:448
	s_waitcnt vmcnt(28)
	ds_write_b128 v185, v[36:39]
	ds_write_b128 v186, v[40:43]
	ds_write_b128 v187, v[44:47]
	ds_write_b128 v188, v[48:51]
	s_and_saveexec_b64 s[36:37], s[8:9]
	s_cbranch_execz .Lgs_595
	v_mul_f32_e32 v130, 0x3fb8aa3b, v196
	v_exp_f32_e32 v130, v130
	ds_write_b128 v189, v[52:55] offset:36864
	ds_write_b32 v161, v130 offset:40960

; #define LAS __attribute__((address_space(3)))
; DI unsigned pk2(float a, float b) { f32x2 v = {a, b}; bf16v2_t r = __builtin_convertvector(v, bf16v2_t); return __builtin_bit_cast(unsigned, r); }
; DI void phase_gla_scan(const Params& p, LAS unsigned char* lds) {
;     ...
;         auto qload = [&](int c, bf16x8 (&q)[8]) {
;             const char* cb = (const char*)(big + (tok0 + (size_t)c * 64) * 6400) + offq;
; #pragma unroll
;             for (int ks = 0; ks < 8; ++ks) q[ks] = *(const bf16x8*)(cb + 64 * ks);
;     ...
;         auto step = [&](int c, const bf16x8 (&qc)[8]) {
;             LAS unsigned char* sb = lds + (c & 1) * SET; LAS unsigned char* stb = lds + ST_OFF + (c & 1) * STB;
; #pragma unroll
;             for (int g = 0; g < 4; ++g) { const f32x4 e = *(LAS const f32x4*)(sb + 64 * KR + 64 * VR + (32 * w + 8 * g + 4 * hh) * 4);
;                 st[4 * g] *= e[0]; st[4 * g + 1] *= e[1]; st[4 * g + 2] *= e[2]; st[4 * g + 3] *= e[3]; }
; #pragma unroll
;             for (int sx = 0; sx < 4; ++sx) {
;                 LAS unsigned char* ka = sb + (16 * sx + 8 * hh + tq) * KR + (32 * w + 16 * blk + 4 * tp) * 2;
;                 LAS unsigned char* va = sb + 64 * KR + (16 * sx + 8 * hh + tq) * VR + (16 * blk + 4 * tp) * 2;
;                 const bf16x8 af = cat4(trread(ka), trread(ka + 4 * KR)), bfv = cat4(trread(va), trread(va + 4 * VR));
;                 st = mfma32(af, bfv, st);
;             }
; #pragma unroll
;             for (int g = 0; g < 4; ++g) { u32x2 wv; wv.x = pk2(st[4 * g], st[4 * g + 1]); wv.y = pk2(st[4 * g + 2], st[4 * g + 3]);
;                 *(LAS u32x2*)(stb + l32 * SR + (32 * w + 8 * g + 4 * hh) * 2) = wv; }
;             asm volatile("s_waitcnt lgkmcnt(0)" ::: "memory");
;             __builtin_amdgcn_s_barrier();
;             asm volatile("" ::: "memory");
;             f32x4 acc = {0.f, 0.f, 0.f, 0.f};
; #pragma unroll
;             for (int ks = 0; ks < 8; ++ks) {
;                 const bf16x8 bb = *(LAS const bf16x8*)(stb + (16 * nt + i16) * SR + (32 * ks + 8 * quad) * 2);
;                 acc = __builtin_amdgcn_mfma_f32_16x16x32_bf16(qc[ks], bb, acc, 0, 0, 0);
;             }
; #pragma unroll
;             for (int jj = 0; jj < 4; ++jj) ob[(tok0 + c * 64 + 16 * mt + quad * 4 + jj) * DM + h * 512 + vs * 32 + 16 * nt + i16] = f2bf(acc[jj] * (1.f / 16.f));
;         };
.Lgs_600:
	ds_read_b128 v[150:153], v176 offset:96
	ds_read_b128 v[154:157], v176 offset:64
	ds_read_b128 v[198:201], v176 offset:32
	ds_read_b128 v[202:205], v176
	s_waitcnt lgkmcnt(3)
	v_pk_mul_f32 v[12:13], v[12:13], v[150:151]
	v_pk_mul_f32 v[14:15], v[14:15], v[152:153]
	ds_read_b64_tr_b16 v[150:151], v190 offset:41984
	ds_read_b64_tr_b16 v[152:153], v190 offset:44288
	s_waitcnt lgkmcnt(4)
	v_pk_mul_f32 v[8:9], v[8:9], v[154:155]
	s_waitcnt lgkmcnt(3)
	v_pk_mul_f32 v[4:5], v[4:5], v[198:199]
	v_pk_mul_f32 v[10:11], v[10:11], v[156:157]
	v_pk_mul_f32 v[6:7], v[6:7], v[200:201]
	s_waitcnt lgkmcnt(2)
	v_pk_mul_f32 v[2:3], v[2:3], v[204:205]
	v_pk_mul_f32 v[0:1], v[0:1], v[202:203]
	ds_read_b64_tr_b16 v[154:155], v177
	ds_read_b64_tr_b16 v[156:157], v177 offset:256
	ds_read_b64_tr_b16 v[198:199], v191 offset:41984
	ds_read_b64_tr_b16 v[200:201], v191 offset:44288
	ds_read_b64_tr_b16 v[202:203], v179
	ds_read_b64_tr_b16 v[204:205], v179 offset:256
	ds_read_b64_tr_b16 v[222:223], v192 offset:41984
	ds_read_b64_tr_b16 v[224:225], v192 offset:44288
	ds_read_b64_tr_b16 v[226:227], v180
	ds_read_b64_tr_b16 v[228:229], v180 offset:256
	s_waitcnt lgkmcnt(8)
	v_mfma_f32_32x32x16_bf16 v[0:15], v[150:153], v[154:157], v[0:15]
	ds_read_b64_tr_b16 v[230:231], v193 offset:41984
	ds_read_b64_tr_b16 v[232:233], v193 offset:44288
	ds_read_b64_tr_b16 v[234:235], v182
	ds_read_b64_tr_b16 v[236:237], v182 offset:256
	s_waitcnt lgkmcnt(8)
	v_mfma_f32_32x32x16_bf16 v[0:15], v[198:201], v[202:205], v[0:15]
	s_waitcnt lgkmcnt(4)
	v_mfma_f32_32x32x16_bf16 v[0:15], v[222:225], v[226:229], v[0:15]
	s_waitcnt lgkmcnt(0)
	v_mfma_f32_32x32x16_bf16 v[0:15], v[230:233], v[234:237], v[0:15]
	v_lshl_add_u64 v[202:203], s[12:13], 0, v[146:147]
	v_add_co_u32_e32 v204, vcc, s46, v202
	s_nop 1
	v_addc_co_u32_e32 v205, vcc, 0, v203, vcc
	v_add_co_u32_e32 v206, vcc, 0x7f42000, v202
	s_nop 5
	v_cvt_pk_bf16_f32 v150, v0, v1
	v_cvt_pk_bf16_f32 v151, v2, v3
	v_cvt_pk_bf16_f32 v152, v4, v5
	v_cvt_pk_bf16_f32 v153, v6, v7
	v_cvt_pk_bf16_f32 v154, v8, v9
	v_cvt_pk_bf16_f32 v155, v10, v11
	v_cvt_pk_bf16_f32 v156, v12, v13
	v_cvt_pk_bf16_f32 v157, v14, v15
	ds_write2_b64 v183, v[150:151], v[152:153] offset1:2
	ds_write2_b64 v183, v[154:155], v[156:157] offset0:4 offset1:6
	s_waitcnt lgkmcnt(0)
	s_barrier
	ds_read_b128 v[222:225], v184
	ds_read_b128 v[226:229], v184 offset:64
	ds_read_b128 v[230:233], v184 offset:128
	ds_read_b128 v[234:237], v184 offset:192
	ds_read_b128 v[238:241], v184 offset:256
	ds_read_b128 v[242:245], v184 offset:320
	ds_read_b128 v[246:249], v184 offset:384
	ds_read_b128 v[250:253], v184 offset:448
	s_waitcnt vmcnt(27) lgkmcnt(7)
	v_mfma_f32_16x16x32_bf16 v[150:153], v[76:79], v[222:225], 0
	v_addc_co_u32_e32 v207, vcc, 0, v203, vcc
	s_waitcnt vmcnt(26) lgkmcnt(6)
	v_mfma_f32_16x16x32_bf16 v[150:153], v[84:87], v[226:229], v[150:153]
	s_waitcnt vmcnt(25) lgkmcnt(5)
	v_mfma_f32_16x16x32_bf16 v[150:153], v[92:95], v[230:233], v[150:153]
	s_waitcnt vmcnt(24) lgkmcnt(4)
	v_mfma_f32_16x16x32_bf16 v[150:153], v[100:103], v[234:237], v[150:153]
	s_waitcnt vmcnt(23) lgkmcnt(3)
	v_mfma_f32_16x16x32_bf16 v[150:153], v[104:107], v[238:241], v[150:153]
	s_waitcnt vmcnt(22) lgkmcnt(2)
	v_mfma_f32_16x16x32_bf16 v[150:153], v[108:111], v[242:245], v[150:153]
	s_waitcnt vmcnt(21) lgkmcnt(1)
	v_mfma_f32_16x16x32_bf16 v[150:153], v[112:115], v[246:249], v[150:153]
	s_waitcnt vmcnt(20) lgkmcnt(0)
	v_mfma_f32_16x16x32_bf16 v[150:153], v[116:119], v[250:253], v[150:153]
	s_nop 7
	v_mul_f32_e32 v130, 0x3d800000, v150
	v_mul_f32_e32 v150, 0x3d800000, v151
	v_mul_f32_e32 v151, 0x3d800000, v152
	v_cvt_pk_bf16_f32 v130, v130, s0
	v_cvt_pk_bf16_f32 v150, v150, s0
	v_cvt_pk_bf16_f32 v151, v151, s0
	global_store_short v[204:205], v130, off offset:-4096
	global_store_short v[204:205], v150, off
	global_store_short v[206:207], v151, off
	v_add_co_u32_e32 v150, vcc, 0x7f43000, v202
	v_mul_f32_e32 v152, 0x3d800000, v153
	s_nop 0
	v_addc_co_u32_e32 v151, vcc, 0, v203, vcc
	v_cvt_pk_bf16_f32 v152, v152, s0
	s_andn2_b64 vcc, exec, s[30:31]
	global_store_short v[150:151], v152, off
	s_cbranch_vccnz .Lgs_585
	v_lshl_add_u64 v[116:117], v[158:159], 0, s[92:93]
	global_load_dwordx4 v[76:79], v[116:117], off
	global_load_dwordx4 v[84:87], v[116:117], off offset:64
	global_load_dwordx4 v[92:95], v[116:117], off offset:128
	global_load_dwordx4 v[100:103], v[116:117], off offset:192
	global_load_dwordx4 v[104:107], v[116:117], off offset:256
	global_load_dwordx4 v[108:111], v[116:117], off offset:320
	global_load_dwordx4 v[112:115], v[116:117], off offset:384
	s_nop 0
	global_load_dwordx4 v[116:119], v[116:117], off offset:448
	s_branch .Lgs_585

; #define LAS __attribute__((address_space(3)))
; DI int otid() { int t = threadIdx.x; asm volatile("" : "+v"(t)); return t; }
; DI void phase_lru_scan(const Params& p, LAS unsigned char* lds) {
;     const unsigned* ax = (const unsigned*)(p.ws + ACT + 128 * MiB); const bf16_t* big = (const bf16_t*)(p.ws + ACT);
;     bf16_t* y = (bf16_t*)(p.ws + HBUF);
;     LAS unsigned* tile = (LAS unsigned*)lds;
;     LAS float* sP = (LAS float*)(lds + 65536); LAS float* sH = sP + 512; LAS float* sC = sH + 512;
;     const int tid = otid(), seg = tid >> 5, chl = tid & 31;
;     for (int u = blockIdx.x; u < 256; u += gridDim.x) {
;         const int b = u >> 6, ch = (u & 63) * 32 + chl;
;         const size_t rowbase = (size_t)b * SEQ;
;         unsigned pre[32];
; #pragma unroll
;         for (int i = 0; i < 32; ++i) pre[i] = ax[(rowbase + seg + 16 * i) * DM + ch];
;         __syncthreads();
;         if (tid < 32) sC[tid] = 0.f;
;         for (int sc = 0; sc < 8; ++sc) {
; #pragma unroll
;             for (int i = 0; i < 32; ++i) tile[(seg + 16 * i) * 32 + chl] = pre[i];
;             __syncthreads();
;             if (sc + 1 < 8) {
; #pragma unroll
;                 for (int i = 0; i < 32; ++i) pre[i] = ax[(rowbase + (sc + 1) * 512 + seg + 16 * i) * DM + ch];
;             }
.LBB0_1009:
	s_or_b64 exec, exec, s[8:9]
	v_mov_b32_e32 v4, v181
	s_and_b64 vcc, exec, s[6:7]
	s_waitcnt lgkmcnt(0)
	s_barrier
	s_cbranch_vccnz .LBB0_1026
	s_cmp_eq_u32 s18, 0x100
	s_cbranch_scc0 .Llr_orig
	s_load_dwordx2 s[6:7], s[0:1], 0xf0
	v_and_b32_e32 v126, 31, v181
	v_lshrrev_b32_e32 v113, 5, v181
	v_lshlrev_b32_e32 v112, 2, v126
	v_lshl_add_u32 v114, v113, 12, v112
	v_lshlrev_b32_e32 v127, 1, v126
	v_lshl_add_u32 v115, v113, 11, v127
	v_add_u32_e32 v115, 65536, v115
	v_lshlrev_b32_e32 v116, 2, v181
	v_add_u32_e32 v116, 98304, v116
	v_add_u32_e32 v117, 98304, v112
	v_lshrrev_b32_e32 v128, 3, v181
	v_and_b32_e32 v129, 7, v181
	v_lshlrev_b32_e32 v118, 7, v128
	v_lshl_add_u32 v118, v129, 4, v118
	v_lshlrev_b32_e32 v120, 13, v128
	v_lshl_add_u32 v120, v129, 4, v120
	v_lshrrev_b32_e32 v128, 2, v181
	v_and_b32_e32 v129, 3, v181
	v_lshlrev_b32_e32 v119, 6, v128
	v_lshl_add_u32 v119, v129, 4, v119
	v_add_u32_e32 v119, 65536, v119
	v_lshlrev_b32_e32 v121, 13, v128
	v_lshl_add_u32 v121, v129, 4, v121
	v_lshlrev_b32_e32 v122, 12, v128
	v_lshl_add_u32 v122, v129, 4, v122
	s_lshr_b32 s10, s2, 3
	s_and_b32 s9, s2, 7
	s_lshr_b32 s8, s10, 3
	s_bfe_u32 s11, s10, 0x20001
	s_lshl_b32 s11, s11, 3
	s_add_u32 s9, s9, s11
	s_lshl_b32 s9, s9, 1
	s_and_b32 s10, s10, 1
	s_or_b32 s9, s9, s10
	s_lshl_b32 s10, s8, 25
	s_lshl_b32 s11, s9, 7
	s_waitcnt lgkmcnt(0)
	s_add_u32 s12, s6, 0x13f00000
	s_addc_u32 s13, s7, 0
	s_add_u32 s12, s12, s10
	s_addc_u32 s13, s13, 0
	s_add_u32 s12, s12, s11
	s_addc_u32 s13, s13, 0
	s_lshl_b32 s11, s9, 6
	s_add_u32 s14, s6, 0xbf01000
	s_addc_u32 s15, s7, 0
	s_add_u32 s14, s14, s10
	s_addc_u32 s15, s15, 0
	s_add_u32 s14, s14, s11
	s_addc_u32 s15, s15, 0
	s_lshl_b32 s10, s8, 24
	s_add_u32 s16, s6, 0x7f00000
	s_addc_u32 s17, s7, 0
	s_add_u32 s16, s16, s10
	s_addc_u32 s17, s17, 0
	s_add_u32 s16, s16, s11
	s_addc_u32 s17, s17, 0
	s_mov_b64 s[24:25], s[12:13]
	global_load_dwordx4 v[64:67], v120, s[24:25]
	s_add_u32 s24, s24, 0x80000
	s_addc_u32 s25, s25, 0
	global_load_dwordx4 v[68:71], v120, s[24:25]
	s_add_u32 s24, s24, 0x80000
	s_addc_u32 s25, s25, 0
	global_load_dwordx4 v[72:75], v120, s[24:25]
	s_add_u32 s24, s24, 0x80000
	s_addc_u32 s25, s25, 0
	global_load_dwordx4 v[76:79], v120, s[24:25]
	s_add_u32 s24, s24, 0x80000
	s_addc_u32 s25, s25, 0
	global_load_dwordx4 v[80:83], v120, s[24:25]
	s_add_u32 s24, s24, 0x80000
	s_addc_u32 s25, s25, 0
	global_load_dwordx4 v[84:87], v120, s[24:25]
	s_add_u32 s24, s24, 0x80000
	s_addc_u32 s25, s25, 0
	global_load_dwordx4 v[88:91], v120, s[24:25]
	s_add_u32 s24, s24, 0x80000
	s_addc_u32 s25, s25, 0
	global_load_dwordx4 v[92:95], v120, s[24:25]
	s_mov_b64 s[24:25], s[14:15]
	global_load_dwordx4 v[96:99], v121, s[24:25]
	s_add_u32 s24, s24, 0x100000
	s_addc_u32 s25, s25, 0
	global_load_dwordx4 v[100:103], v121, s[24:25]
	s_add_u32 s24, s24, 0x100000
	s_addc_u32 s25, s25, 0
	global_load_dwordx4 v[104:107], v121, s[24:25]
	s_add_u32 s24, s24, 0x100000
	s_addc_u32 s25, s25, 0
	global_load_dwordx4 v[108:111], v121, s[24:25]
	s_add_u32 s12, s12, 0x400000
	s_addc_u32 s13, s13, 0
	s_add_u32 s14, s14, 0x400000
	s_addc_u32 s15, s15, 0
	v_cmp_gt_u32_e32 vcc, 32, v181
	s_and_saveexec_b64 s[26:27], vcc
	v_mov_b32_e32 v126, 0
	v_add_u32_e32 v127, 102400, v112
	ds_write_b32 v127, v126
	s_mov_b64 exec, s[26:27]
	s_mov_b64 exec, -1
	s_mov_b32 s28, 0
	s_waitcnt vmcnt(0)
.Llr_sc:
	s_barrier
	s_waitcnt vmcnt(4)
	ds_write_b128 v118, v[64:67] offset:0
	ds_write_b128 v118, v[68:71] offset:8192
	ds_write_b128 v118, v[72:75] offset:16384
	ds_write_b128 v118, v[76:79] offset:24576
	ds_write_b128 v118, v[80:83] offset:32768
	ds_write_b128 v118, v[84:87] offset:40960
	ds_write_b128 v118, v[88:91] offset:49152
	ds_write_b128 v118, v[92:95] offset:57344
	ds_write_b128 v119, v[96:99] offset:0
	ds_write_b128 v119, v[100:103] offset:8192
	ds_write_b128 v119, v[104:107] offset:16384
	ds_write_b128 v119, v[108:111] offset:24576
	s_waitcnt lgkmcnt(0)
	s_barrier
	s_cmp_eq_u32 s28, 7
	s_cbranch_scc1 .Llr_noload
	s_mov_b64 s[24:25], s[12:13]
	global_load_dwordx4 v[64:67], v120, s[24:25]
	s_add_u32 s24, s24, 0x80000
	s_addc_u32 s25, s25, 0
	global_load_dwordx4 v[68:71], v120, s[24:25]
	s_add_u32 s24, s24, 0x80000
	s_addc_u32 s25, s25, 0
	global_load_dwordx4 v[72:75], v120, s[24:25]
	s_add_u32 s24, s24, 0x80000
	s_addc_u32 s25, s25, 0
	global_load_dwordx4 v[76:79], v120, s[24:25]
	s_add_u32 s24, s24, 0x80000
	s_addc_u32 s25, s25, 0
	global_load_dwordx4 v[80:83], v120, s[24:25]
	s_add_u32 s24, s24, 0x80000
	s_addc_u32 s25, s25, 0
	global_load_dwordx4 v[84:87], v120, s[24:25]
	s_add_u32 s24, s24, 0x80000
	s_addc_u32 s25, s25, 0
	global_load_dwordx4 v[88:91], v120, s[24:25]
	s_add_u32 s24, s24, 0x80000
	s_addc_u32 s25, s25, 0
	global_load_dwordx4 v[92:95], v120, s[24:25]
	s_mov_b64 s[24:25], s[14:15]
	global_load_dwordx4 v[96:99], v121, s[24:25]
	s_add_u32 s24, s24, 0x100000
	s_addc_u32 s25, s25, 0
	global_load_dwordx4 v[100:103], v121, s[24:25]
	s_add_u32 s24, s24, 0x100000
	s_addc_u32 s25, s25, 0
	global_load_dwordx4 v[104:107], v121, s[24:25]
	s_add_u32 s24, s24, 0x100000
	s_addc_u32 s25, s25, 0
	global_load_dwordx4 v[108:111], v121, s[24:25]
	s_add_u32 s12, s12, 0x400000
	s_addc_u32 s13, s13, 0
	s_add_u32 s14, s14, 0x400000
	s_addc_u32 s15, s15, 0
